# S5 carry scan placed on the XCD class that produced the chunk states and consumes the carries
# speedup vs baseline: 1.0316x; 1.0011x over previous
.LBB0_544:
	s_or_b64 exec, exec, s[0:1]
	s_waitcnt lgkmcnt(0)
	s_and_b32 s98, s6, 7
	s_lshl_b32 s98, s98, 5
	s_lshr_b32 s99, s6, 3
	s_add_i32 s98, s98, s99
	v_mov_b32_e32 v0, 0x6050400
	v_perm_b32 v0, s98, v193, v0
	v_and_b32_e32 v1, 0x300, v193
	v_mad_u64_u32 v[0:1], s[0:1], s92, v1, v[0:1]
	s_mov_b32 s2, 0x10000
	v_cmp_gt_i32_e32 vcc, s2, v0
	v_and_b32_e32 v192, 63, v193
	s_barrier
	s_and_saveexec_b64 s[0:1], vcc
	s_cbranch_execz .LBB0_551
	v_mov_b32_e32 v3, 0
	v_lshlrev_b32_e32 v2, 3, v192
	v_lshl_add_u64 v[4:5], s[90:91], 0, v[2:3]
	s_mov_b64 s[4:5], 0x3fe0000
	s_lshl_b32 s3, s92, 9
	v_lshl_add_u64 v[4:5], v[4:5], 0, s[4:5]
	s_mov_b64 s[4:5], 0
	s_movk_i32 s7, 0x4000
	s_movk_i32 s12, 0x3c0
	v_lshlrev_b32_e32 v6, 2, v192
	v_mov_b32_e32 v7, v3
	s_movk_i32 s13, 0x600
	v_mov_b64_e32 v[8:9], s[90:91]
	v_lshlrev_b32_e32 v10, 1, v192
	v_mov_b32_e32 v11, v3
	s_mov_b64 s[8:9], 0x88f0400
	s_movk_i32 s14, 0x1000
	s_movk_i32 s15, 0x2000
	s_movk_i32 s16, 0x3000
	s_movk_i32 s17, 0x5000
	s_movk_i32 s33, 0x6000
	s_movk_i32 s34, 0x7000
	s_mov_b32 s35, 0x8000
	s_mov_b32 s38, 0x9000
	s_mov_b32 s39, 0xa000
	s_mov_b32 s40, 0xb000
	s_mov_b32 s41, 0xc000
	s_mov_b32 s42, 0xd000
	s_mov_b32 s43, 0xe000
	s_mov_b32 s44, 0xf000
	s_mov_b32 s45, 0x17000
	s_mov_b32 s48, 0x16000
	s_mov_b32 s49, 0x15000
	s_mov_b32 s50, 0x14000
	s_mov_b32 s51, 0x13000
	s_mov_b32 s54, 0x12000
	s_mov_b32 s55, 0x11000
	s_mov_b32 s56, 0xffff
	s_branch .LBB0_547
